# v5 + swa_unit K/V staging: six exec-masked tile loads issued together before one wait
# speedup vs baseline: 1.0025x; 1.0025x over previous
; #define LAS __attribute__((address_space(3)))
; __device__ __forceinline__ void swa_unit(Frame& F, const int jl, const int unit) {
;     const int kv = unit % 3, blk = (unit / 3) & 63, b = unit / 192;
;     const bf16* P = (const bf16*)(F.ws + WS_PROJ); bf16* CAT = (bf16*)(F.ws + WS_CAT);
;     const int p0 = blk * 64; const size_t rowb = (size_t)b * SEQ;
;     const ldsp Ks = F.lds, Vt = F.lds + 27648;
;     constexpr int KP = 144, VP = 392;
; #pragma unroll
;     for (int q = 0; q < 3; ++q) { const int p = F.tid + 512 * q, key = p >> 3, c = p & 7, pos = p0 - 128 + key;
;         v4u val = (v4u){0u, 0u, 0u, 0u}; if (pos >= 0) val = *(const v4u*)(P + (rowb + pos) * SWA_NP + S_K + kv * 64 + 8 * c);
;         *(LAS v4u*)(Ks + key * KP + c * 16) = val; }
; #pragma unroll
;     for (int q = 0; q < 3; ++q) { const int p = F.tid + 512 * q, key = p % 192, c = p / 192, pos = p0 - 128 + key;
;         v4u val = (v4u){0u, 0u, 0u, 0u}; if (pos >= 0) val = *(const v4u*)(P + (rowb + pos) * SWA_NP + S_V + kv * 64 + 8 * c);
;         const ldsp vb = Vt + (8 * c) * VP + key * 2;
;         *(LAS bf16*)(vb) = (bf16)(val.x & 0xffff); *(LAS bf16*)(vb + VP) = (bf16)(val.x >> 16); *(LAS bf16*)(vb + 2 * VP) = (bf16)(val.y & 0xffff); *(LAS bf16*)(vb + 3 * VP) = (bf16)(val.y >> 16);
;         *(LAS bf16*)(vb + 4 * VP) = (bf16)(val.z & 0xffff); *(LAS bf16*)(vb + 5 * VP) = (bf16)(val.z >> 16); *(LAS bf16*)(vb + 6 * VP) = (bf16)(val.w & 0xffff); *(LAS bf16*)(vb + 7 * VP) = (bf16)(val.w >> 16); }
;     __syncthreads();
;     const int r = F.lane & 31, h = F.lane >> 5, head = kv * 8 + F.wave;
;     const float slope = exp2f(-8.0f * (float)(head + 1) / 24.0f), sink = F.in[9][jl * 24 + head];
.LBB0_348:
	s_mul_hi_i32 s10, s26, 0x55555556
	s_lshr_b32 s11, s10, 31
	s_add_i32 s10, s10, s11
	s_mul_i32 s11, s10, 3
	s_sub_i32 s12, s26, s11
	s_mul_hi_i32 s11, s26, 0x2aaaaaab
	s_lshr_b32 s13, s11, 31
	s_ashr_i32 s11, s11, 5
	s_lshl_b32 s10, s10, 6
	s_add_i32 s14, s11, s13
	s_and_b32 s10, s10, 0xfc0
	s_ashr_i32 s15, s14, 31
	s_add_i32 s11, s10, 0xffffff80
	s_lshl_b64 s[92:93], s[14:15], 12
	s_lshl_b32 s14, s12, 6
	v_add_u32_e32 v8, s11, v107
	s_ashr_i32 s15, s14, 31
	v_cmp_lt_i32_e32 vcc, -1, v8
	v_mov_b32_e32 v0, 0
	v_lshlrev_b32_e32 v6, 1, v86
	v_mov_b32_e32 v2, 0
	v_mov_b32_e32 v3, 0
	v_mov_b32_e32 v4, 0
	v_mov_b32_e32 v5, 0
	v_mov_b32_e32 v208, 0
	v_mov_b32_e32 v209, 0
	v_mov_b32_e32 v210, 0
	v_mov_b32_e32 v211, 0
	s_and_saveexec_b64 s[18:19], vcc
	s_cbranch_execz .LBB0_350
	v_mov_b32_e32 v9, v96
	v_lshl_add_u64 v[2:3], s[92:93], 0, v[8:9]
	v_mov_b64_e32 v[4:5], s[4:5]
	v_mad_u64_u32 v[4:5], vcc, v2, s74, v[4:5]
	v_mad_i32_i24 v5, v3, s74, v5
	v_lshl_add_u64 v[2:3], s[14:15], 1, v[4:5]
	v_mov_b32_e32 v7, v96
	v_lshl_add_u64 v[2:3], v[2:3], 0, v[6:7]
	flat_load_dwordx4 v[208:211], v[2:3] offset:3072
.LBB0_350:
	s_or_b64 exec, exec, s[18:19]
	v_add_u32_e32 v4, s11, v108
	v_cmp_lt_i32_e32 vcc, -1, v4
	v_mov_b32_e32 v1, 0
	v_mov_b32_e32 v2, 0
	v_mov_b32_e32 v3, 0
	v_mov_b32_e32 v212, 0
	v_mov_b32_e32 v213, 0
	v_mov_b32_e32 v214, 0
	v_mov_b32_e32 v215, 0
	s_and_saveexec_b64 s[18:19], vcc
	s_cbranch_execz .LBB0_352
	v_mov_b32_e32 v5, v96
	v_lshl_add_u64 v[0:1], s[92:93], 0, v[4:5]
	v_mov_b64_e32 v[2:3], s[4:5]
	v_mad_u64_u32 v[2:3], vcc, v0, s74, v[2:3]
	v_mad_i32_i24 v3, v1, s74, v3
	v_lshl_add_u64 v[0:1], s[14:15], 1, v[2:3]
	v_mov_b32_e32 v7, v96
	v_lshl_add_u64 v[0:1], v[0:1], 0, v[6:7]
	flat_load_dwordx4 v[212:215], v[0:1] offset:3072
.LBB0_352:
	s_or_b64 exec, exec, s[18:19]
	v_add_u32_e32 v8, s11, v109
	v_cmp_lt_i32_e32 vcc, -1, v8
	v_mov_b32_e32 v0, 0
	v_mov_b32_e32 v2, 0
	v_mov_b32_e32 v3, 0
	v_mov_b32_e32 v4, 0
	v_mov_b32_e32 v5, 0
	v_mov_b32_e32 v216, 0
	v_mov_b32_e32 v217, 0
	v_mov_b32_e32 v218, 0
	v_mov_b32_e32 v219, 0
	s_and_saveexec_b64 s[18:19], vcc
	s_cbranch_execz .LBB0_354
	v_mov_b32_e32 v9, v96
	v_lshl_add_u64 v[2:3], s[92:93], 0, v[8:9]
	v_mov_b64_e32 v[4:5], s[4:5]
	v_mad_u64_u32 v[4:5], vcc, v2, s74, v[4:5]
	v_mad_i32_i24 v5, v3, s74, v5
	v_lshl_add_u64 v[2:3], s[14:15], 1, v[4:5]
	v_mov_b32_e32 v7, v96
	v_lshl_add_u64 v[2:3], v[2:3], 0, v[6:7]
	flat_load_dwordx4 v[216:219], v[2:3] offset:3072
.LBB0_354:
	s_or_b64 exec, exec, s[18:19]
	v_add_u32_e32 v4, s11, v110
	v_cmp_lt_i32_e32 vcc, -1, v4
	v_mov_b32_e32 v1, 0
	v_mov_b32_e32 v2, 0
	v_mov_b32_e32 v3, 0
	v_mov_b32_e32 v220, 0
	v_mov_b32_e32 v221, 0
	v_mov_b32_e32 v222, 0
	v_mov_b32_e32 v223, 0
	s_and_saveexec_b64 s[18:19], vcc
	s_cbranch_execz .LBB0_356
	v_mov_b32_e32 v5, v96
	v_lshl_add_u64 v[0:1], s[92:93], 0, v[4:5]
	v_mov_b64_e32 v[2:3], s[4:5]
	v_mad_u64_u32 v[2:3], vcc, v0, s74, v[2:3]
	v_mad_i32_i24 v3, v1, s74, v3
	v_lshl_add_u64 v[0:1], s[14:15], 1, v[2:3]
	v_lshl_add_u64 v[0:1], v[88:89], 1, v[0:1]
	flat_load_dwordx4 v[220:223], v[0:1] offset:3456
.LBB0_356:
	s_or_b64 exec, exec, s[18:19]
	v_add_u32_e32 v6, s11, v111
	v_cmp_lt_i32_e32 vcc, -1, v6
	v_mov_b32_e32 v0, 0
	v_mov_b32_e32 v2, 0
	v_mov_b32_e32 v3, 0
	v_mov_b32_e32 v4, 0
	v_mov_b32_e32 v5, 0
	v_mov_b32_e32 v224, 0
	v_mov_b32_e32 v225, 0
	v_mov_b32_e32 v226, 0
	v_mov_b32_e32 v227, 0
	s_and_saveexec_b64 s[18:19], vcc
	s_cbranch_execz .LBB0_358
	v_mov_b32_e32 v7, v96
	v_lshl_add_u64 v[2:3], s[92:93], 0, v[6:7]
	v_mov_b64_e32 v[4:5], s[4:5]
	v_mad_u64_u32 v[4:5], vcc, v2, s74, v[4:5]
	v_mad_i32_i24 v5, v3, s74, v5
	v_lshl_add_u64 v[2:3], s[14:15], 1, v[4:5]
	v_lshl_add_u64 v[2:3], v[90:91], 1, v[2:3]
	flat_load_dwordx4 v[224:227], v[2:3] offset:3456
.LBB0_358:
	s_or_b64 exec, exec, s[18:19]
	v_add_u32_e32 v4, s11, v112
	v_cmp_lt_i32_e32 vcc, -1, v4
	s_mov_b32 s11, 0
	v_mov_b32_e32 v1, 0
	v_mov_b32_e32 v2, 0
	v_mov_b32_e32 v3, 0
	v_mov_b32_e32 v228, 0
	v_mov_b32_e32 v229, 0
	v_mov_b32_e32 v230, 0
	v_mov_b32_e32 v231, 0
	s_and_saveexec_b64 s[18:19], vcc
	s_cbranch_execz .LBB0_360
	v_mov_b32_e32 v5, v96
	v_lshl_add_u64 v[0:1], s[92:93], 0, v[4:5]
	v_mov_b64_e32 v[2:3], s[4:5]
	v_mad_u64_u32 v[2:3], vcc, v0, s74, v[2:3]
	v_mad_i32_i24 v3, v1, s74, v3
	v_lshl_add_u64 v[0:1], s[14:15], 1, v[2:3]
	v_lshl_add_u64 v[0:1], v[92:93], 1, v[0:1]
	flat_load_dwordx4 v[228:231], v[0:1] offset:3456
.LBB0_360:
	s_or_b64 exec, exec, s[18:19]
	s_lshl_b32 s12, s12, 3
	s_add_i32 s12, s12, s9
	s_add_i32 s13, s12, 1
	v_cvt_f32_i32_e32 v0, s13
	s_mov_b32 s13, 0xc2fc0000
	s_waitcnt vmcnt(0) lgkmcnt(0)
	ds_write_b128 v115, v[208:211]
	ds_write_b128 v116, v[212:215]
	ds_write_b128 v117, v[216:219]
	ds_write_b16 v118, v220 offset:27648
	ds_write_b16_d16_hi v118, v220 offset:28040
	ds_write_b16 v118, v221 offset:28432
	ds_write_b16_d16_hi v118, v221 offset:28824
	ds_write_b16 v118, v222 offset:29216
	ds_write_b16_d16_hi v118, v222 offset:29608
	ds_write_b16 v118, v223 offset:30000
	ds_write_b16_d16_hi v118, v223 offset:30392
	ds_write_b16 v119, v224 offset:27648
	ds_write_b16_d16_hi v119, v224 offset:28040
	ds_write_b16 v119, v225 offset:28432
	ds_write_b16_d16_hi v119, v225 offset:28824
	ds_write_b16 v119, v226 offset:29216
	ds_write_b16_d16_hi v119, v226 offset:29608
	ds_write_b16 v119, v227 offset:30000
	ds_write_b16_d16_hi v119, v227 offset:30392
	ds_write_b16 v120, v228 offset:27648
	ds_write_b16_d16_hi v120, v228 offset:28040
	ds_write_b16 v120, v229 offset:28432
	ds_write_b16_d16_hi v120, v229 offset:28824
	ds_write_b16 v120, v230 offset:29216
	ds_write_b16_d16_hi v120, v230 offset:29608
	ds_write_b16 v120, v231 offset:30000
	ds_write_b16_d16_hi v120, v231 offset:30392
	s_waitcnt lgkmcnt(0)
	s_barrier
	v_mul_f32_e32 v0, 0xc1000000, v0
	v_div_scale_f32 v1, s[14:15], s38, s38, v0
	v_rcp_f32_e32 v2, v1
	s_nop 0
	v_fma_f32 v3, -v1, v2, 1.0
	v_fmac_f32_e32 v2, v3, v2
	v_div_scale_f32 v3, vcc, v0, s38, v0
	v_mul_f32_e32 v4, v3, v2
	v_fma_f32 v5, -v1, v4, v3
	v_fmac_f32_e32 v4, v5, v2
	v_fma_f32 v1, -v1, v4, v3
	v_div_fmas_f32 v1, v1, v2, v4
	v_div_fixup_f32 v0, v1, s38, v0
	v_cmp_gt_f32_e32 vcc, s13, v0
	v_mov_b32_e32 v1, 0x42800000
	s_and_b64 s[14:15], vcc, exec
	v_cndmask_b32_e32 v1, 0, v1, vcc
	v_add_f32_e32 v0, v0, v1
	v_exp_f32_e32 v0, v0
	s_cselect_b32 s13, 0xffffffc0, 0
	v_ldexp_f32 v121, v0, s13
	v_mov_b64_e32 v[0:1], s[0:1]
	flat_load_dwordx2 v[0:1], v[0:1] offset:72
	s_mul_i32 s13, s7, 24
	s_add_i32 s14, s12, s13
	s_ashr_i32 s15, s14, 31
	s_lshl_b32 s12, s12, 6
	s_ashr_i32 s13, s12, 31
	s_lshl_b64 s[12:13], s[12:13], 1
	v_lshl_add_u64 v[100:101], v[94:95], 0, s[12:13]
	v_lshl_add_u64 v[102:103], v[98:99], 0, s[12:13]
	s_waitcnt vmcnt(0) lgkmcnt(0)
	v_lshl_add_u64 v[0:1], s[14:15], 2, v[0:1]
	flat_load_dword v122, v[0:1]
	s_mov_b64 s[14:15], -1
